# P3 epilogue rewritten: residual loads pipelined 5 row groups ahead + full 128-byte-line loads/stores via DPP row_ror:8 piece exchange (f32, bf16 copy and row sum-of-squares handled in the exchanged la
# speedup vs baseline: 1.0088x; 1.0088x over previous
; DI unsigned cvt_pk(float lo, float hi) { const f32x2 v = {lo, hi}; return __builtin_bit_cast(unsigned, __builtin_convertvector(v, bf16v2)); }
;     __device__ __forceinline__ void operator()(const f32x4 (&acc)[2][2][4][2], const Unit& u, int wr, int wc, int fr, int fq) const {
;         const int col0 = u.pn * 256 + wc * 32 + 8 * fq, rowbase = u.pm * 256 + wr * 64 + fr;
; #pragma unroll
;         for (int ai = 0; ai < 2; ++ai)
; #pragma unroll
;             for (int m = 0; m < 4; ++m) {
;                 const int row = rowbase + ai * 128 + m * 16; const size_t off = (size_t)row * DM + col0;
;                 float q = 0.f;
; #pragma unroll
;                 for (int bj = 0; bj < 2; ++bj) {
;                     const f32x4 r0 = *(const f32x4*)(resid + off + bj * 128), r1 = *(const f32x4*)(resid + off + bj * 128 + 4);
;                     const f32x4 o0 = r0 + acc[ai][bj][m][0], o1 = r1 + acc[ai][bj][m][1];
;                     *(f32x4*)(out + off + bj * 128) = o0; *(f32x4*)(out + off + bj * 128 + 4) = o1;
;                     if (xb) {
;                         u32x4 w; w.x = cvt_pk(o0[0], o0[1]); w.y = cvt_pk(o0[2], o0[3]); w.z = cvt_pk(o1[0], o1[1]); w.w = cvt_pk(o1[2], o1[3]);
;                         *(u32x4*)(xb + off + bj * 128) = w;
;                         q += (o0[0] * o0[0] + o0[1] * o0[1]) + (o0[2] * o0[2] + o0[3] * o0[3]) + (o1[0] * o1[0] + o1[1] * o1[1]) + (o1[2] * o1[2] + o1[3] * o1[3]);
;                     }
;                 }
;                 if (xb) { q += __shfl_xor(q, 16); q += __shfl_xor(q, 32); if (fq == 0) ssq[(size_t)row * 16 + u.pn * 4 + wc] = q; }
.LBB0_753:
	v_lshl_add_u32 v146, s60, 8, v148
	v_lshl_or_b32 v145, s8, 8, v150
	v_lshl_add_u32 v144, v146, 10, v145
	v_lshlrev_b32_e32 v144, 2, v144
	s_lshl_b32 s60, s8, 4
	s_lshl_b32 s61, s33, 2
	s_add_i32 s60, s60, s61
	v_lshl_add_u32 v147, v146, 6, s60
	v_xor_b32_e32 v250, 16, v154
	v_xor_b32_e32 v251, 32, v154
	v_lshlrev_b32_e32 v250, 2, v250
	v_lshlrev_b32_e32 v251, 2, v251
	v_and_b32_e32 v155, 8, v154
	v_mul_i32_i24_e32 v155, 0xfffff002, v155
	v_add_u32_e32 v144, v144, v155
	v_add_u32_e32 v253, 0x8000, v144
	global_load_dwordx4 v[156:159], v144, s[52:53]
	global_load_dwordx4 v[160:163], v253, s[52:53]
	global_load_dwordx4 v[164:167], v144, s[52:53] offset:512
	global_load_dwordx4 v[168:171], v253, s[52:53] offset:512
	v_add_u32_e32 v252, 0x10000, v144
	v_add_u32_e32 v253, 0x8000, v252
	global_load_dwordx4 v[172:175], v252, s[52:53]
	global_load_dwordx4 v[176:179], v253, s[52:53]
	global_load_dwordx4 v[180:183], v252, s[52:53] offset:512
	global_load_dwordx4 v[184:187], v253, s[52:53] offset:512
	v_add_u32_e32 v252, 0x20000, v144
	v_add_u32_e32 v253, 0x8000, v252
	global_load_dwordx4 v[188:191], v252, s[52:53]
	global_load_dwordx4 v[192:195], v253, s[52:53]
	global_load_dwordx4 v[196:199], v252, s[52:53] offset:512
	global_load_dwordx4 v[200:203], v253, s[52:53] offset:512
	v_add_u32_e32 v252, 0x30000, v144
	v_add_u32_e32 v253, 0x8000, v252
	global_load_dwordx4 v[204:207], v252, s[52:53]
	global_load_dwordx4 v[208:211], v253, s[52:53]
	global_load_dwordx4 v[212:215], v252, s[52:53] offset:512
	global_load_dwordx4 v[216:219], v253, s[52:53] offset:512
	v_add_u32_e32 v252, 0x80000, v144
	v_add_u32_e32 v253, 0x8000, v252
	global_load_dwordx4 v[220:223], v252, s[52:53]
	global_load_dwordx4 v[226:229], v253, s[52:53]
	global_load_dwordx4 v[230:233], v252, s[52:53] offset:512
	global_load_dwordx4 v[236:239], v253, s[52:53] offset:512
	v_mov_b32_dpp v240, v120 row_ror:8 row_mask:0xf bank_mask:0xf
	v_mov_b32_dpp v241, v121 row_ror:8 row_mask:0xf bank_mask:0xf
	v_mov_b32_dpp v242, v122 row_ror:8 row_mask:0xf bank_mask:0xf
	v_mov_b32_dpp v243, v123 row_ror:8 row_mask:0xf bank_mask:0xf
	v_mov_b32_dpp v120, v124 row_ror:8 row_mask:0xf bank_mask:0x3
	v_mov_b32_dpp v121, v125 row_ror:8 row_mask:0xf bank_mask:0x3
	v_mov_b32_dpp v122, v126 row_ror:8 row_mask:0xf bank_mask:0x3
	v_mov_b32_dpp v123, v127 row_ror:8 row_mask:0xf bank_mask:0x3
	v_mov_b32_dpp v124, v240 quad_perm:[0,1,2,3] row_mask:0xf bank_mask:0xc
	v_mov_b32_dpp v125, v241 quad_perm:[0,1,2,3] row_mask:0xf bank_mask:0xc
	v_mov_b32_dpp v126, v242 quad_perm:[0,1,2,3] row_mask:0xf bank_mask:0xc
	v_mov_b32_dpp v127, v243 quad_perm:[0,1,2,3] row_mask:0xf bank_mask:0xc
	v_mov_b32_dpp v240, v112 row_ror:8 row_mask:0xf bank_mask:0xf
	v_mov_b32_dpp v241, v113 row_ror:8 row_mask:0xf bank_mask:0xf
	v_mov_b32_dpp v242, v114 row_ror:8 row_mask:0xf bank_mask:0xf
	v_mov_b32_dpp v243, v115 row_ror:8 row_mask:0xf bank_mask:0xf
	v_mov_b32_dpp v112, v116 row_ror:8 row_mask:0xf bank_mask:0x3
	v_mov_b32_dpp v113, v117 row_ror:8 row_mask:0xf bank_mask:0x3
	v_mov_b32_dpp v114, v118 row_ror:8 row_mask:0xf bank_mask:0x3
	v_mov_b32_dpp v115, v119 row_ror:8 row_mask:0xf bank_mask:0x3
	v_mov_b32_dpp v116, v240 quad_perm:[0,1,2,3] row_mask:0xf bank_mask:0xc
	v_mov_b32_dpp v117, v241 quad_perm:[0,1,2,3] row_mask:0xf bank_mask:0xc
	v_mov_b32_dpp v118, v242 quad_perm:[0,1,2,3] row_mask:0xf bank_mask:0xc
	v_mov_b32_dpp v119, v243 quad_perm:[0,1,2,3] row_mask:0xf bank_mask:0xc
	s_waitcnt vmcnt(16)
	v_pk_add_f32 v[124:125], v[124:125], v[156:157]
	v_pk_add_f32 v[126:127], v[126:127], v[158:159]
	v_pk_add_f32 v[120:121], v[120:121], v[160:161]
	v_pk_add_f32 v[122:123], v[122:123], v[162:163]
	v_pk_add_f32 v[116:117], v[116:117], v[164:165]
	v_pk_add_f32 v[118:119], v[118:119], v[166:167]
	v_pk_add_f32 v[112:113], v[112:113], v[168:169]
	v_pk_add_f32 v[114:115], v[114:115], v[170:171]
	v_add_u32_e32 v253, 0x8000, v144
	global_store_dwordx4 v144, v[124:127], s[54:55]
	global_store_dwordx4 v253, v[120:123], s[54:55]
	global_store_dwordx4 v144, v[116:119], s[54:55] offset:512
	global_store_dwordx4 v253, v[112:115], s[54:55] offset:512
	v_cvt_pk_bf16_f32 v240, v124, v125
	v_cvt_pk_bf16_f32 v241, v126, v127
	v_cvt_pk_bf16_f32 v242, v120, v121
	v_cvt_pk_bf16_f32 v243, v122, v123
	v_cvt_pk_bf16_f32 v244, v116, v117
	v_cvt_pk_bf16_f32 v245, v118, v119
	v_cvt_pk_bf16_f32 v246, v112, v113
	v_cvt_pk_bf16_f32 v247, v114, v115
	v_lshrrev_b32_e32 v254, 1, v144
	v_lshrrev_b32_e32 v253, 1, v253
	global_store_dwordx2 v254, v[240:241], s[40:41]
	global_store_dwordx2 v253, v[242:243], s[40:41]
	global_store_dwordx2 v254, v[244:245], s[40:41] offset:256
	global_store_dwordx2 v253, v[246:247], s[40:41] offset:256
	v_mul_f32_e32 v248, v124, v124
	v_mul_f32_e32 v249, v120, v120
	v_fmac_f32_e32 v248, v125, v125
	v_fmac_f32_e32 v249, v121, v121
	v_fmac_f32_e32 v248, v126, v126
	v_fmac_f32_e32 v249, v122, v122
	v_fmac_f32_e32 v248, v127, v127
	v_fmac_f32_e32 v249, v123, v123
	v_fmac_f32_e32 v248, v116, v116
	v_fmac_f32_e32 v249, v112, v112
	v_fmac_f32_e32 v248, v117, v117
	v_fmac_f32_e32 v249, v113, v113
	v_fmac_f32_e32 v248, v118, v118
	v_fmac_f32_e32 v249, v114, v114
	v_fmac_f32_e32 v248, v119, v119
	v_fmac_f32_e32 v249, v115, v115
	s_nop 1
	v_mov_b32_dpp v240, v248 row_ror:8 row_mask:0xf bank_mask:0xf
	v_mov_b32_dpp v241, v249 row_ror:8 row_mask:0xf bank_mask:0xf
	s_nop 0
	v_add_f32_e32 v248, v248, v240
	v_add_f32_e32 v249, v249, v241
	s_nop 1
	v_mov_b32_dpp v248, v249 quad_perm:[0,1,2,3] row_mask:0xf bank_mask:0xc
	ds_bpermute_b32 v249, v250, v248
	s_waitcnt lgkmcnt(0)
	v_add_f32_e32 v248, v248, v249
	ds_bpermute_b32 v249, v251, v248
	s_waitcnt lgkmcnt(0)
; DI unsigned cvt_pk(float lo, float hi) { const f32x2 v = {lo, hi}; return __builtin_bit_cast(unsigned, __builtin_convertvector(v, bf16v2)); }
;     __device__ __forceinline__ void operator()(const f32x4 (&acc)[2][2][4][2], const Unit& u, int wr, int wc, int fr, int fq) const {
;         const int col0 = u.pn * 256 + wc * 32 + 8 * fq, rowbase = u.pm * 256 + wr * 64 + fr;
; #pragma unroll
;         for (int ai = 0; ai < 2; ++ai)
; #pragma unroll
;             for (int m = 0; m < 4; ++m) {
;                 const int row = rowbase + ai * 128 + m * 16; const size_t off = (size_t)row * DM + col0;
;                 float q = 0.f;
; #pragma unroll
;                 for (int bj = 0; bj < 2; ++bj) {
;                     const f32x4 r0 = *(const f32x4*)(resid + off + bj * 128), r1 = *(const f32x4*)(resid + off + bj * 128 + 4);
;                     const f32x4 o0 = r0 + acc[ai][bj][m][0], o1 = r1 + acc[ai][bj][m][1];
;                     *(f32x4*)(out + off + bj * 128) = o0; *(f32x4*)(out + off + bj * 128 + 4) = o1;
;                     if (xb) {
;                         u32x4 w; w.x = cvt_pk(o0[0], o0[1]); w.y = cvt_pk(o0[2], o0[3]); w.z = cvt_pk(o1[0], o1[1]); w.w = cvt_pk(o1[2], o1[3]);
;                         *(u32x4*)(xb + off + bj * 128) = w;
;                         q += (o0[0] * o0[0] + o0[1] * o0[1]) + (o0[2] * o0[2] + o0[3] * o0[3]) + (o1[0] * o1[0] + o1[1] * o1[1]) + (o1[2] * o1[2] + o1[3] * o1[3]);
;                     }
;                 }
;                 if (xb) { q += __shfl_xor(q, 16); q += __shfl_xor(q, 32); if (fq == 0) ssq[(size_t)row * 16 + u.pn * 4 + wc] = q; }
	v_add_f32_e32 v248, v248, v249
	s_and_saveexec_b64 s[62:63], s[0:1]
	global_store_dword v147, v248, s[6:7]
	s_or_b64 exec, exec, s[62:63]
	v_add_u32_e32 v252, 0x90000, v144
	v_add_u32_e32 v253, 0x8000, v252
	global_load_dwordx4 v[156:159], v252, s[52:53]
	global_load_dwordx4 v[160:163], v253, s[52:53]
	global_load_dwordx4 v[164:167], v252, s[52:53] offset:512
	global_load_dwordx4 v[168:171], v253, s[52:53] offset:512
	v_mov_b32_dpp v240, v104 row_ror:8 row_mask:0xf bank_mask:0xf
	v_mov_b32_dpp v241, v105 row_ror:8 row_mask:0xf bank_mask:0xf
	v_mov_b32_dpp v242, v106 row_ror:8 row_mask:0xf bank_mask:0xf
	v_mov_b32_dpp v243, v107 row_ror:8 row_mask:0xf bank_mask:0xf
	v_mov_b32_dpp v104, v108 row_ror:8 row_mask:0xf bank_mask:0x3
	v_mov_b32_dpp v105, v109 row_ror:8 row_mask:0xf bank_mask:0x3
	v_mov_b32_dpp v106, v110 row_ror:8 row_mask:0xf bank_mask:0x3
	v_mov_b32_dpp v107, v111 row_ror:8 row_mask:0xf bank_mask:0x3
	v_mov_b32_dpp v108, v240 quad_perm:[0,1,2,3] row_mask:0xf bank_mask:0xc
	v_mov_b32_dpp v109, v241 quad_perm:[0,1,2,3] row_mask:0xf bank_mask:0xc
	v_mov_b32_dpp v110, v242 quad_perm:[0,1,2,3] row_mask:0xf bank_mask:0xc
	v_mov_b32_dpp v111, v243 quad_perm:[0,1,2,3] row_mask:0xf bank_mask:0xc
	v_mov_b32_dpp v240, v96 row_ror:8 row_mask:0xf bank_mask:0xf
	v_mov_b32_dpp v241, v97 row_ror:8 row_mask:0xf bank_mask:0xf
	v_mov_b32_dpp v242, v98 row_ror:8 row_mask:0xf bank_mask:0xf
	v_mov_b32_dpp v243, v99 row_ror:8 row_mask:0xf bank_mask:0xf
	v_mov_b32_dpp v96, v100 row_ror:8 row_mask:0xf bank_mask:0x3
	v_mov_b32_dpp v97, v101 row_ror:8 row_mask:0xf bank_mask:0x3
	v_mov_b32_dpp v98, v102 row_ror:8 row_mask:0xf bank_mask:0x3
	v_mov_b32_dpp v99, v103 row_ror:8 row_mask:0xf bank_mask:0x3
	v_mov_b32_dpp v100, v240 quad_perm:[0,1,2,3] row_mask:0xf bank_mask:0xc
	v_mov_b32_dpp v101, v241 quad_perm:[0,1,2,3] row_mask:0xf bank_mask:0xc
	v_mov_b32_dpp v102, v242 quad_perm:[0,1,2,3] row_mask:0xf bank_mask:0xc
	v_mov_b32_dpp v103, v243 quad_perm:[0,1,2,3] row_mask:0xf bank_mask:0xc
	s_waitcnt vmcnt(25)
	v_pk_add_f32 v[108:109], v[108:109], v[172:173]
	v_pk_add_f32 v[110:111], v[110:111], v[174:175]
	v_pk_add_f32 v[104:105], v[104:105], v[176:177]
	v_pk_add_f32 v[106:107], v[106:107], v[178:179]
	v_pk_add_f32 v[100:101], v[100:101], v[180:181]
	v_pk_add_f32 v[102:103], v[102:103], v[182:183]
	v_pk_add_f32 v[96:97], v[96:97], v[184:185]
	v_pk_add_f32 v[98:99], v[98:99], v[186:187]
	v_add_u32_e32 v252, 0x10000, v144
	v_add_u32_e32 v253, 0x8000, v252
	global_store_dwordx4 v252, v[108:111], s[54:55]
	global_store_dwordx4 v253, v[104:107], s[54:55]
	global_store_dwordx4 v252, v[100:103], s[54:55] offset:512
	global_store_dwordx4 v253, v[96:99], s[54:55] offset:512
	v_cvt_pk_bf16_f32 v240, v108, v109
	v_cvt_pk_bf16_f32 v241, v110, v111
	v_cvt_pk_bf16_f32 v242, v104, v105
	v_cvt_pk_bf16_f32 v243, v106, v107
	v_cvt_pk_bf16_f32 v244, v100, v101
	v_cvt_pk_bf16_f32 v245, v102, v103
	v_cvt_pk_bf16_f32 v246, v96, v97
	v_cvt_pk_bf16_f32 v247, v98, v99
	v_lshrrev_b32_e32 v254, 1, v252
	v_lshrrev_b32_e32 v253, 1, v253
	global_store_dwordx2 v254, v[240:241], s[40:41]
	global_store_dwordx2 v253, v[242:243], s[40:41]
	global_store_dwordx2 v254, v[244:245], s[40:41] offset:256
	global_store_dwordx2 v253, v[246:247], s[40:41] offset:256
	v_mul_f32_e32 v248, v108, v108
	v_mul_f32_e32 v249, v104, v104
	v_fmac_f32_e32 v248, v109, v109
	v_fmac_f32_e32 v249, v105, v105
	v_fmac_f32_e32 v248, v110, v110
	v_fmac_f32_e32 v249, v106, v106
	v_fmac_f32_e32 v248, v111, v111
	v_fmac_f32_e32 v249, v107, v107
	v_fmac_f32_e32 v248, v100, v100
	v_fmac_f32_e32 v249, v96, v96
	v_fmac_f32_e32 v248, v101, v101
	v_fmac_f32_e32 v249, v97, v97
	v_fmac_f32_e32 v248, v102, v102
	v_fmac_f32_e32 v249, v98, v98
	v_fmac_f32_e32 v248, v103, v103
	v_fmac_f32_e32 v249, v99, v99
	s_nop 1
	v_mov_b32_dpp v240, v248 row_ror:8 row_mask:0xf bank_mask:0xf
	v_mov_b32_dpp v241, v249 row_ror:8 row_mask:0xf bank_mask:0xf
	s_nop 0
	v_add_f32_e32 v248, v248, v240
	v_add_f32_e32 v249, v249, v241
	s_nop 1
	v_mov_b32_dpp v248, v249 quad_perm:[0,1,2,3] row_mask:0xf bank_mask:0xc
	ds_bpermute_b32 v249, v250, v248
	s_waitcnt lgkmcnt(0)
	v_add_f32_e32 v248, v248, v249
	ds_bpermute_b32 v249, v251, v248
	v_add_u32_e32 v254, 0x400, v147
	s_waitcnt lgkmcnt(0)
	v_add_f32_e32 v248, v248, v249
	s_and_saveexec_b64 s[62:63], s[0:1]
	global_store_dword v254, v248, s[6:7]
	s_or_b64 exec, exec, s[62:63]
	v_add_u32_e32 v252, 0xa0000, v144
	v_add_u32_e32 v253, 0x8000, v252
	global_load_dwordx4 v[172:175], v252, s[52:53]
	global_load_dwordx4 v[176:179], v253, s[52:53]
	global_load_dwordx4 v[180:183], v252, s[52:53] offset:512
	global_load_dwordx4 v[184:187], v253, s[52:53] offset:512
	v_mov_b32_dpp v240, v88 row_ror:8 row_mask:0xf bank_mask:0xf
	v_mov_b32_dpp v241, v89 row_ror:8 row_mask:0xf bank_mask:0xf
	v_mov_b32_dpp v242, v90 row_ror:8 row_mask:0xf bank_mask:0xf
	v_mov_b32_dpp v243, v91 row_ror:8 row_mask:0xf bank_mask:0xf
	v_mov_b32_dpp v88, v92 row_ror:8 row_mask:0xf bank_mask:0x3
	v_mov_b32_dpp v89, v93 row_ror:8 row_mask:0xf bank_mask:0x3
	v_mov_b32_dpp v90, v94 row_ror:8 row_mask:0xf bank_mask:0x3
	v_mov_b32_dpp v91, v95 row_ror:8 row_mask:0xf bank_mask:0x3
	v_mov_b32_dpp v92, v240 quad_perm:[0,1,2,3] row_mask:0xf bank_mask:0xc
	v_mov_b32_dpp v93, v241 quad_perm:[0,1,2,3] row_mask:0xf bank_mask:0xc
	v_mov_b32_dpp v94, v242 quad_perm:[0,1,2,3] row_mask:0xf bank_mask:0xc
	v_mov_b32_dpp v95, v243 quad_perm:[0,1,2,3] row_mask:0xf bank_mask:0xc
	v_mov_b32_dpp v240, v80 row_ror:8 row_mask:0xf bank_mask:0xf
	v_mov_b32_dpp v241, v81 row_ror:8 row_mask:0xf bank_mask:0xf
	v_mov_b32_dpp v242, v82 row_ror:8 row_mask:0xf bank_mask:0xf
	v_mov_b32_dpp v243, v83 row_ror:8 row_mask:0xf bank_mask:0xf
	v_mov_b32_dpp v80, v84 row_ror:8 row_mask:0xf bank_mask:0x3
	v_mov_b32_dpp v81, v85 row_ror:8 row_mask:0xf bank_mask:0x3
	v_mov_b32_dpp v82, v86 row_ror:8 row_mask:0xf bank_mask:0x3
	v_mov_b32_dpp v83, v87 row_ror:8 row_mask:0xf bank_mask:0x3
	v_mov_b32_dpp v84, v240 quad_perm:[0,1,2,3] row_mask:0xf bank_mask:0xc
	v_mov_b32_dpp v85, v241 quad_perm:[0,1,2,3] row_mask:0xf bank_mask:0xc
	v_mov_b32_dpp v86, v242 quad_perm:[0,1,2,3] row_mask:0xf bank_mask:0xc
	v_mov_b32_dpp v87, v243 quad_perm:[0,1,2,3] row_mask:0xf bank_mask:0xc
	s_waitcnt vmcnt(34)
; DI unsigned cvt_pk(float lo, float hi) { const f32x2 v = {lo, hi}; return __builtin_bit_cast(unsigned, __builtin_convertvector(v, bf16v2)); }
;     __device__ __forceinline__ void operator()(const f32x4 (&acc)[2][2][4][2], const Unit& u, int wr, int wc, int fr, int fq) const {
;         const int col0 = u.pn * 256 + wc * 32 + 8 * fq, rowbase = u.pm * 256 + wr * 64 + fr;
; #pragma unroll
;         for (int ai = 0; ai < 2; ++ai)
; #pragma unroll
;             for (int m = 0; m < 4; ++m) {
;                 const int row = rowbase + ai * 128 + m * 16; const size_t off = (size_t)row * DM + col0;
;                 float q = 0.f;
; #pragma unroll
;                 for (int bj = 0; bj < 2; ++bj) {
;                     const f32x4 r0 = *(const f32x4*)(resid + off + bj * 128), r1 = *(const f32x4*)(resid + off + bj * 128 + 4);
;                     const f32x4 o0 = r0 + acc[ai][bj][m][0], o1 = r1 + acc[ai][bj][m][1];
;                     *(f32x4*)(out + off + bj * 128) = o0; *(f32x4*)(out + off + bj * 128 + 4) = o1;
;                     if (xb) {
;                         u32x4 w; w.x = cvt_pk(o0[0], o0[1]); w.y = cvt_pk(o0[2], o0[3]); w.z = cvt_pk(o1[0], o1[1]); w.w = cvt_pk(o1[2], o1[3]);
;                         *(u32x4*)(xb + off + bj * 128) = w;
;                         q += (o0[0] * o0[0] + o0[1] * o0[1]) + (o0[2] * o0[2] + o0[3] * o0[3]) + (o1[0] * o1[0] + o1[1] * o1[1]) + (o1[2] * o1[2] + o1[3] * o1[3]);
;                     }
;                 }
;                 if (xb) { q += __shfl_xor(q, 16); q += __shfl_xor(q, 32); if (fq == 0) ssq[(size_t)row * 16 + u.pn * 4 + wc] = q; }
	v_pk_add_f32 v[92:93], v[92:93], v[188:189]
	v_pk_add_f32 v[94:95], v[94:95], v[190:191]
	v_pk_add_f32 v[88:89], v[88:89], v[192:193]
	v_pk_add_f32 v[90:91], v[90:91], v[194:195]
	v_pk_add_f32 v[84:85], v[84:85], v[196:197]
	v_pk_add_f32 v[86:87], v[86:87], v[198:199]
	v_pk_add_f32 v[80:81], v[80:81], v[200:201]
	v_pk_add_f32 v[82:83], v[82:83], v[202:203]
	v_add_u32_e32 v252, 0x20000, v144
	v_add_u32_e32 v253, 0x8000, v252
	global_store_dwordx4 v252, v[92:95], s[54:55]
	global_store_dwordx4 v253, v[88:91], s[54:55]
	global_store_dwordx4 v252, v[84:87], s[54:55] offset:512
	global_store_dwordx4 v253, v[80:83], s[54:55] offset:512
	v_cvt_pk_bf16_f32 v240, v92, v93
	v_cvt_pk_bf16_f32 v241, v94, v95
	v_cvt_pk_bf16_f32 v242, v88, v89
	v_cvt_pk_bf16_f32 v243, v90, v91
	v_cvt_pk_bf16_f32 v244, v84, v85
	v_cvt_pk_bf16_f32 v245, v86, v87
	v_cvt_pk_bf16_f32 v246, v80, v81
	v_cvt_pk_bf16_f32 v247, v82, v83
	v_lshrrev_b32_e32 v254, 1, v252
	v_lshrrev_b32_e32 v253, 1, v253
	global_store_dwordx2 v254, v[240:241], s[40:41]
	global_store_dwordx2 v253, v[242:243], s[40:41]
	global_store_dwordx2 v254, v[244:245], s[40:41] offset:256
	global_store_dwordx2 v253, v[246:247], s[40:41] offset:256
	v_mul_f32_e32 v248, v92, v92
	v_mul_f32_e32 v249, v88, v88
	v_fmac_f32_e32 v248, v93, v93
	v_fmac_f32_e32 v249, v89, v89
	v_fmac_f32_e32 v248, v94, v94
	v_fmac_f32_e32 v249, v90, v90
	v_fmac_f32_e32 v248, v95, v95
	v_fmac_f32_e32 v249, v91, v91
	v_fmac_f32_e32 v248, v84, v84
	v_fmac_f32_e32 v249, v80, v80
	v_fmac_f32_e32 v248, v85, v85
	v_fmac_f32_e32 v249, v81, v81
	v_fmac_f32_e32 v248, v86, v86
	v_fmac_f32_e32 v249, v82, v82
	v_fmac_f32_e32 v248, v87, v87
	v_fmac_f32_e32 v249, v83, v83
	s_nop 1
	v_mov_b32_dpp v240, v248 row_ror:8 row_mask:0xf bank_mask:0xf
	v_mov_b32_dpp v241, v249 row_ror:8 row_mask:0xf bank_mask:0xf
	s_nop 0
	v_add_f32_e32 v248, v248, v240
	v_add_f32_e32 v249, v249, v241
	s_nop 1
	v_mov_b32_dpp v248, v249 quad_perm:[0,1,2,3] row_mask:0xf bank_mask:0xc
	ds_bpermute_b32 v249, v250, v248
	s_waitcnt lgkmcnt(0)
	v_add_f32_e32 v248, v248, v249
	ds_bpermute_b32 v249, v251, v248
	v_add_u32_e32 v254, 0x800, v147
	s_waitcnt lgkmcnt(0)
	v_add_f32_e32 v248, v248, v249
	s_and_saveexec_b64 s[62:63], s[0:1]
	global_store_dword v254, v248, s[6:7]
	s_or_b64 exec, exec, s[62:63]
	v_add_u32_e32 v252, 0xb0000, v144
	v_add_u32_e32 v253, 0x8000, v252
	global_load_dwordx4 v[188:191], v252, s[52:53]
	global_load_dwordx4 v[192:195], v253, s[52:53]
	global_load_dwordx4 v[196:199], v252, s[52:53] offset:512
	global_load_dwordx4 v[200:203], v253, s[52:53] offset:512
	v_mov_b32_dpp v240, v72 row_ror:8 row_mask:0xf bank_mask:0xf
	v_mov_b32_dpp v241, v73 row_ror:8 row_mask:0xf bank_mask:0xf
	v_mov_b32_dpp v242, v74 row_ror:8 row_mask:0xf bank_mask:0xf
	v_mov_b32_dpp v243, v75 row_ror:8 row_mask:0xf bank_mask:0xf
	v_mov_b32_dpp v72, v76 row_ror:8 row_mask:0xf bank_mask:0x3
	v_mov_b32_dpp v73, v77 row_ror:8 row_mask:0xf bank_mask:0x3
	v_mov_b32_dpp v74, v78 row_ror:8 row_mask:0xf bank_mask:0x3
	v_mov_b32_dpp v75, v79 row_ror:8 row_mask:0xf bank_mask:0x3
	v_mov_b32_dpp v76, v240 quad_perm:[0,1,2,3] row_mask:0xf bank_mask:0xc
	v_mov_b32_dpp v77, v241 quad_perm:[0,1,2,3] row_mask:0xf bank_mask:0xc
	v_mov_b32_dpp v78, v242 quad_perm:[0,1,2,3] row_mask:0xf bank_mask:0xc
	v_mov_b32_dpp v79, v243 quad_perm:[0,1,2,3] row_mask:0xf bank_mask:0xc
	v_mov_b32_dpp v240, v64 row_ror:8 row_mask:0xf bank_mask:0xf
	v_mov_b32_dpp v241, v65 row_ror:8 row_mask:0xf bank_mask:0xf
	v_mov_b32_dpp v242, v66 row_ror:8 row_mask:0xf bank_mask:0xf
	v_mov_b32_dpp v243, v67 row_ror:8 row_mask:0xf bank_mask:0xf
	v_mov_b32_dpp v64, v68 row_ror:8 row_mask:0xf bank_mask:0x3
	v_mov_b32_dpp v65, v69 row_ror:8 row_mask:0xf bank_mask:0x3
	v_mov_b32_dpp v66, v70 row_ror:8 row_mask:0xf bank_mask:0x3
	v_mov_b32_dpp v67, v71 row_ror:8 row_mask:0xf bank_mask:0x3
	v_mov_b32_dpp v68, v240 quad_perm:[0,1,2,3] row_mask:0xf bank_mask:0xc
	v_mov_b32_dpp v69, v241 quad_perm:[0,1,2,3] row_mask:0xf bank_mask:0xc
	v_mov_b32_dpp v70, v242 quad_perm:[0,1,2,3] row_mask:0xf bank_mask:0xc
	v_mov_b32_dpp v71, v243 quad_perm:[0,1,2,3] row_mask:0xf bank_mask:0xc
	s_waitcnt vmcnt(43)
	v_pk_add_f32 v[76:77], v[76:77], v[204:205]
	v_pk_add_f32 v[78:79], v[78:79], v[206:207]
	v_pk_add_f32 v[72:73], v[72:73], v[208:209]
	v_pk_add_f32 v[74:75], v[74:75], v[210:211]
	v_pk_add_f32 v[68:69], v[68:69], v[212:213]
	v_pk_add_f32 v[70:71], v[70:71], v[214:215]
	v_pk_add_f32 v[64:65], v[64:65], v[216:217]
	v_pk_add_f32 v[66:67], v[66:67], v[218:219]
	v_add_u32_e32 v252, 0x30000, v144
	v_add_u32_e32 v253, 0x8000, v252
	global_store_dwordx4 v252, v[76:79], s[54:55]
	global_store_dwordx4 v253, v[72:75], s[54:55]
	global_store_dwordx4 v252, v[68:71], s[54:55] offset:512
	global_store_dwordx4 v253, v[64:67], s[54:55] offset:512
	v_cvt_pk_bf16_f32 v240, v76, v77
	v_cvt_pk_bf16_f32 v241, v78, v79
	v_cvt_pk_bf16_f32 v242, v72, v73
	v_cvt_pk_bf16_f32 v243, v74, v75
	v_cvt_pk_bf16_f32 v244, v68, v69
	v_cvt_pk_bf16_f32 v245, v70, v71
	v_cvt_pk_bf16_f32 v246, v64, v65
	v_cvt_pk_bf16_f32 v247, v66, v67
	v_lshrrev_b32_e32 v254, 1, v252
	v_lshrrev_b32_e32 v253, 1, v253
	global_store_dwordx2 v254, v[240:241], s[40:41]
	global_store_dwordx2 v253, v[242:243], s[40:41]
	global_store_dwordx2 v254, v[244:245], s[40:41] offset:256
	global_store_dwordx2 v253, v[246:247], s[40:41] offset:256
	v_mul_f32_e32 v248, v76, v76
	v_mul_f32_e32 v249, v72, v72
	v_fmac_f32_e32 v248, v77, v77
	v_fmac_f32_e32 v249, v73, v73
	v_fmac_f32_e32 v248, v78, v78
	v_fmac_f32_e32 v249, v74, v74
	v_fmac_f32_e32 v248, v79, v79
	v_fmac_f32_e32 v249, v75, v75
	v_fmac_f32_e32 v248, v68, v68
	v_fmac_f32_e32 v249, v64, v64
	v_fmac_f32_e32 v248, v69, v69
	v_fmac_f32_e32 v249, v65, v65
	v_fmac_f32_e32 v248, v70, v70
	v_fmac_f32_e32 v249, v66, v66
	v_fmac_f32_e32 v248, v71, v71
	v_fmac_f32_e32 v249, v67, v67
	s_nop 1
	v_mov_b32_dpp v240, v248 row_ror:8 row_mask:0xf bank_mask:0xf
	v_mov_b32_dpp v241, v249 row_ror:8 row_mask:0xf bank_mask:0xf
	s_nop 0
	v_add_f32_e32 v248, v248, v240
	v_add_f32_e32 v249, v249, v241
	s_nop 1
	v_mov_b32_dpp v248, v249 quad_perm:[0,1,2,3] row_mask:0xf bank_mask:0xc
	ds_bpermute_b32 v249, v250, v248
	s_waitcnt lgkmcnt(0)
; DI unsigned cvt_pk(float lo, float hi) { const f32x2 v = {lo, hi}; return __builtin_bit_cast(unsigned, __builtin_convertvector(v, bf16v2)); }
;     __device__ __forceinline__ void operator()(const f32x4 (&acc)[2][2][4][2], const Unit& u, int wr, int wc, int fr, int fq) const {
;         const int col0 = u.pn * 256 + wc * 32 + 8 * fq, rowbase = u.pm * 256 + wr * 64 + fr;
; #pragma unroll
;         for (int ai = 0; ai < 2; ++ai)
; #pragma unroll
;             for (int m = 0; m < 4; ++m) {
;                 const int row = rowbase + ai * 128 + m * 16; const size_t off = (size_t)row * DM + col0;
;                 float q = 0.f;
; #pragma unroll
;                 for (int bj = 0; bj < 2; ++bj) {
;                     const f32x4 r0 = *(const f32x4*)(resid + off + bj * 128), r1 = *(const f32x4*)(resid + off + bj * 128 + 4);
;                     const f32x4 o0 = r0 + acc[ai][bj][m][0], o1 = r1 + acc[ai][bj][m][1];
;                     *(f32x4*)(out + off + bj * 128) = o0; *(f32x4*)(out + off + bj * 128 + 4) = o1;
;                     if (xb) {
;                         u32x4 w; w.x = cvt_pk(o0[0], o0[1]); w.y = cvt_pk(o0[2], o0[3]); w.z = cvt_pk(o1[0], o1[1]); w.w = cvt_pk(o1[2], o1[3]);
;                         *(u32x4*)(xb + off + bj * 128) = w;
;                         q += (o0[0] * o0[0] + o0[1] * o0[1]) + (o0[2] * o0[2] + o0[3] * o0[3]) + (o1[0] * o1[0] + o1[1] * o1[1]) + (o1[2] * o1[2] + o1[3] * o1[3]);
;                     }
;                 }
;                 if (xb) { q += __shfl_xor(q, 16); q += __shfl_xor(q, 32); if (fq == 0) ssq[(size_t)row * 16 + u.pn * 4 + wc] = q; }
	v_add_f32_e32 v248, v248, v249
	ds_bpermute_b32 v249, v251, v248
	v_add_u32_e32 v254, 0xc00, v147
	s_waitcnt lgkmcnt(0)
	v_add_f32_e32 v248, v248, v249
	s_and_saveexec_b64 s[62:63], s[0:1]
	global_store_dword v254, v248, s[6:7]
	s_or_b64 exec, exec, s[62:63]
	v_mov_b32_dpp v240, v56 row_ror:8 row_mask:0xf bank_mask:0xf
	v_mov_b32_dpp v241, v57 row_ror:8 row_mask:0xf bank_mask:0xf
	v_mov_b32_dpp v242, v58 row_ror:8 row_mask:0xf bank_mask:0xf
	v_mov_b32_dpp v243, v59 row_ror:8 row_mask:0xf bank_mask:0xf
	v_mov_b32_dpp v56, v60 row_ror:8 row_mask:0xf bank_mask:0x3
	v_mov_b32_dpp v57, v61 row_ror:8 row_mask:0xf bank_mask:0x3
	v_mov_b32_dpp v58, v62 row_ror:8 row_mask:0xf bank_mask:0x3
	v_mov_b32_dpp v59, v63 row_ror:8 row_mask:0xf bank_mask:0x3
	v_mov_b32_dpp v60, v240 quad_perm:[0,1,2,3] row_mask:0xf bank_mask:0xc
	v_mov_b32_dpp v61, v241 quad_perm:[0,1,2,3] row_mask:0xf bank_mask:0xc
	v_mov_b32_dpp v62, v242 quad_perm:[0,1,2,3] row_mask:0xf bank_mask:0xc
	v_mov_b32_dpp v63, v243 quad_perm:[0,1,2,3] row_mask:0xf bank_mask:0xc
	v_mov_b32_dpp v240, v48 row_ror:8 row_mask:0xf bank_mask:0xf
	v_mov_b32_dpp v241, v49 row_ror:8 row_mask:0xf bank_mask:0xf
	v_mov_b32_dpp v242, v50 row_ror:8 row_mask:0xf bank_mask:0xf
	v_mov_b32_dpp v243, v51 row_ror:8 row_mask:0xf bank_mask:0xf
	v_mov_b32_dpp v48, v52 row_ror:8 row_mask:0xf bank_mask:0x3
	v_mov_b32_dpp v49, v53 row_ror:8 row_mask:0xf bank_mask:0x3
	v_mov_b32_dpp v50, v54 row_ror:8 row_mask:0xf bank_mask:0x3
	v_mov_b32_dpp v51, v55 row_ror:8 row_mask:0xf bank_mask:0x3
	v_mov_b32_dpp v52, v240 quad_perm:[0,1,2,3] row_mask:0xf bank_mask:0xc
	v_mov_b32_dpp v53, v241 quad_perm:[0,1,2,3] row_mask:0xf bank_mask:0xc
	v_mov_b32_dpp v54, v242 quad_perm:[0,1,2,3] row_mask:0xf bank_mask:0xc
	v_mov_b32_dpp v55, v243 quad_perm:[0,1,2,3] row_mask:0xf bank_mask:0xc
	s_waitcnt vmcnt(48)
	v_pk_add_f32 v[60:61], v[60:61], v[220:221]
	v_pk_add_f32 v[62:63], v[62:63], v[222:223]
	v_pk_add_f32 v[56:57], v[56:57], v[226:227]
	v_pk_add_f32 v[58:59], v[58:59], v[228:229]
	v_pk_add_f32 v[52:53], v[52:53], v[230:231]
	v_pk_add_f32 v[54:55], v[54:55], v[232:233]
	v_pk_add_f32 v[48:49], v[48:49], v[236:237]
	v_pk_add_f32 v[50:51], v[50:51], v[238:239]
	v_add_u32_e32 v252, 0x80000, v144
	v_add_u32_e32 v253, 0x8000, v252
	global_store_dwordx4 v252, v[60:63], s[54:55]
	global_store_dwordx4 v253, v[56:59], s[54:55]
	global_store_dwordx4 v252, v[52:55], s[54:55] offset:512
	global_store_dwordx4 v253, v[48:51], s[54:55] offset:512
	v_cvt_pk_bf16_f32 v240, v60, v61
	v_cvt_pk_bf16_f32 v241, v62, v63
	v_cvt_pk_bf16_f32 v242, v56, v57
	v_cvt_pk_bf16_f32 v243, v58, v59
	v_cvt_pk_bf16_f32 v244, v52, v53
	v_cvt_pk_bf16_f32 v245, v54, v55
	v_cvt_pk_bf16_f32 v246, v48, v49
	v_cvt_pk_bf16_f32 v247, v50, v51
	v_lshrrev_b32_e32 v254, 1, v252
	v_lshrrev_b32_e32 v253, 1, v253
	global_store_dwordx2 v254, v[240:241], s[40:41]
	global_store_dwordx2 v253, v[242:243], s[40:41]
	global_store_dwordx2 v254, v[244:245], s[40:41] offset:256
	global_store_dwordx2 v253, v[246:247], s[40:41] offset:256
	v_mul_f32_e32 v248, v60, v60
	v_mul_f32_e32 v249, v56, v56
	v_fmac_f32_e32 v248, v61, v61
	v_fmac_f32_e32 v249, v57, v57
	v_fmac_f32_e32 v248, v62, v62
	v_fmac_f32_e32 v249, v58, v58
	v_fmac_f32_e32 v248, v63, v63
	v_fmac_f32_e32 v249, v59, v59
	v_fmac_f32_e32 v248, v52, v52
	v_fmac_f32_e32 v249, v48, v48
	v_fmac_f32_e32 v248, v53, v53
	v_fmac_f32_e32 v249, v49, v49
	v_fmac_f32_e32 v248, v54, v54
	v_fmac_f32_e32 v249, v50, v50
	v_fmac_f32_e32 v248, v55, v55
	v_fmac_f32_e32 v249, v51, v51
	s_nop 1
	v_mov_b32_dpp v240, v248 row_ror:8 row_mask:0xf bank_mask:0xf
	v_mov_b32_dpp v241, v249 row_ror:8 row_mask:0xf bank_mask:0xf
	s_nop 0
	v_add_f32_e32 v248, v248, v240
	v_add_f32_e32 v249, v249, v241
	s_nop 1
	v_mov_b32_dpp v248, v249 quad_perm:[0,1,2,3] row_mask:0xf bank_mask:0xc
	ds_bpermute_b32 v249, v250, v248
	s_waitcnt lgkmcnt(0)
	v_add_f32_e32 v248, v248, v249
	ds_bpermute_b32 v249, v251, v248
	v_add_u32_e32 v254, 0x2000, v147
	s_waitcnt lgkmcnt(0)
	v_add_f32_e32 v248, v248, v249
	s_and_saveexec_b64 s[62:63], s[0:1]
	global_store_dword v254, v248, s[6:7]
	s_or_b64 exec, exec, s[62:63]
	v_mov_b32_dpp v240, v40 row_ror:8 row_mask:0xf bank_mask:0xf
	v_mov_b32_dpp v241, v41 row_ror:8 row_mask:0xf bank_mask:0xf
	v_mov_b32_dpp v242, v42 row_ror:8 row_mask:0xf bank_mask:0xf
	v_mov_b32_dpp v243, v43 row_ror:8 row_mask:0xf bank_mask:0xf
	v_mov_b32_dpp v40, v44 row_ror:8 row_mask:0xf bank_mask:0x3
	v_mov_b32_dpp v41, v45 row_ror:8 row_mask:0xf bank_mask:0x3
	v_mov_b32_dpp v42, v46 row_ror:8 row_mask:0xf bank_mask:0x3
	v_mov_b32_dpp v43, v47 row_ror:8 row_mask:0xf bank_mask:0x3
	v_mov_b32_dpp v44, v240 quad_perm:[0,1,2,3] row_mask:0xf bank_mask:0xc
	v_mov_b32_dpp v45, v241 quad_perm:[0,1,2,3] row_mask:0xf bank_mask:0xc
	v_mov_b32_dpp v46, v242 quad_perm:[0,1,2,3] row_mask:0xf bank_mask:0xc
	v_mov_b32_dpp v47, v243 quad_perm:[0,1,2,3] row_mask:0xf bank_mask:0xc
	v_mov_b32_dpp v240, v32 row_ror:8 row_mask:0xf bank_mask:0xf
	v_mov_b32_dpp v241, v33 row_ror:8 row_mask:0xf bank_mask:0xf
	v_mov_b32_dpp v242, v34 row_ror:8 row_mask:0xf bank_mask:0xf
	v_mov_b32_dpp v243, v35 row_ror:8 row_mask:0xf bank_mask:0xf
	v_mov_b32_dpp v32, v36 row_ror:8 row_mask:0xf bank_mask:0x3
	v_mov_b32_dpp v33, v37 row_ror:8 row_mask:0xf bank_mask:0x3
	v_mov_b32_dpp v34, v38 row_ror:8 row_mask:0xf bank_mask:0x3
	v_mov_b32_dpp v35, v39 row_ror:8 row_mask:0xf bank_mask:0x3
	v_mov_b32_dpp v36, v240 quad_perm:[0,1,2,3] row_mask:0xf bank_mask:0xc
	v_mov_b32_dpp v37, v241 quad_perm:[0,1,2,3] row_mask:0xf bank_mask:0xc
	v_mov_b32_dpp v38, v242 quad_perm:[0,1,2,3] row_mask:0xf bank_mask:0xc
	v_mov_b32_dpp v39, v243 quad_perm:[0,1,2,3] row_mask:0xf bank_mask:0xc
	s_waitcnt vmcnt(44)
; DI unsigned cvt_pk(float lo, float hi) { const f32x2 v = {lo, hi}; return __builtin_bit_cast(unsigned, __builtin_convertvector(v, bf16v2)); }
;     __device__ __forceinline__ void operator()(const f32x4 (&acc)[2][2][4][2], const Unit& u, int wr, int wc, int fr, int fq) const {
;         const int col0 = u.pn * 256 + wc * 32 + 8 * fq, rowbase = u.pm * 256 + wr * 64 + fr;
; #pragma unroll
;         for (int ai = 0; ai < 2; ++ai)
; #pragma unroll
;             for (int m = 0; m < 4; ++m) {
;                 const int row = rowbase + ai * 128 + m * 16; const size_t off = (size_t)row * DM + col0;
;                 float q = 0.f;
; #pragma unroll
;                 for (int bj = 0; bj < 2; ++bj) {
;                     const f32x4 r0 = *(const f32x4*)(resid + off + bj * 128), r1 = *(const f32x4*)(resid + off + bj * 128 + 4);
;                     const f32x4 o0 = r0 + acc[ai][bj][m][0], o1 = r1 + acc[ai][bj][m][1];
;                     *(f32x4*)(out + off + bj * 128) = o0; *(f32x4*)(out + off + bj * 128 + 4) = o1;
;                     if (xb) {
;                         u32x4 w; w.x = cvt_pk(o0[0], o0[1]); w.y = cvt_pk(o0[2], o0[3]); w.z = cvt_pk(o1[0], o1[1]); w.w = cvt_pk(o1[2], o1[3]);
;                         *(u32x4*)(xb + off + bj * 128) = w;
;                         q += (o0[0] * o0[0] + o0[1] * o0[1]) + (o0[2] * o0[2] + o0[3] * o0[3]) + (o1[0] * o1[0] + o1[1] * o1[1]) + (o1[2] * o1[2] + o1[3] * o1[3]);
;                     }
;                 }
;                 if (xb) { q += __shfl_xor(q, 16); q += __shfl_xor(q, 32); if (fq == 0) ssq[(size_t)row * 16 + u.pn * 4 + wc] = q; }
	v_pk_add_f32 v[44:45], v[44:45], v[156:157]
	v_pk_add_f32 v[46:47], v[46:47], v[158:159]
	v_pk_add_f32 v[40:41], v[40:41], v[160:161]
	v_pk_add_f32 v[42:43], v[42:43], v[162:163]
	v_pk_add_f32 v[36:37], v[36:37], v[164:165]
	v_pk_add_f32 v[38:39], v[38:39], v[166:167]
	v_pk_add_f32 v[32:33], v[32:33], v[168:169]
	v_pk_add_f32 v[34:35], v[34:35], v[170:171]
	v_add_u32_e32 v252, 0x90000, v144
	v_add_u32_e32 v253, 0x8000, v252
	global_store_dwordx4 v252, v[44:47], s[54:55]
	global_store_dwordx4 v253, v[40:43], s[54:55]
	global_store_dwordx4 v252, v[36:39], s[54:55] offset:512
	global_store_dwordx4 v253, v[32:35], s[54:55] offset:512
	v_cvt_pk_bf16_f32 v240, v44, v45
	v_cvt_pk_bf16_f32 v241, v46, v47
	v_cvt_pk_bf16_f32 v242, v40, v41
	v_cvt_pk_bf16_f32 v243, v42, v43
	v_cvt_pk_bf16_f32 v244, v36, v37
	v_cvt_pk_bf16_f32 v245, v38, v39
	v_cvt_pk_bf16_f32 v246, v32, v33
	v_cvt_pk_bf16_f32 v247, v34, v35
	v_lshrrev_b32_e32 v254, 1, v252
	v_lshrrev_b32_e32 v253, 1, v253
	global_store_dwordx2 v254, v[240:241], s[40:41]
	global_store_dwordx2 v253, v[242:243], s[40:41]
	global_store_dwordx2 v254, v[244:245], s[40:41] offset:256
	global_store_dwordx2 v253, v[246:247], s[40:41] offset:256
	v_mul_f32_e32 v248, v44, v44
	v_mul_f32_e32 v249, v40, v40
	v_fmac_f32_e32 v248, v45, v45
	v_fmac_f32_e32 v249, v41, v41
	v_fmac_f32_e32 v248, v46, v46
	v_fmac_f32_e32 v249, v42, v42
	v_fmac_f32_e32 v248, v47, v47
	v_fmac_f32_e32 v249, v43, v43
	v_fmac_f32_e32 v248, v36, v36
	v_fmac_f32_e32 v249, v32, v32
	v_fmac_f32_e32 v248, v37, v37
	v_fmac_f32_e32 v249, v33, v33
	v_fmac_f32_e32 v248, v38, v38
	v_fmac_f32_e32 v249, v34, v34
	v_fmac_f32_e32 v248, v39, v39
	v_fmac_f32_e32 v249, v35, v35
	s_nop 1
	v_mov_b32_dpp v240, v248 row_ror:8 row_mask:0xf bank_mask:0xf
	v_mov_b32_dpp v241, v249 row_ror:8 row_mask:0xf bank_mask:0xf
	s_nop 0
	v_add_f32_e32 v248, v248, v240
	v_add_f32_e32 v249, v249, v241
	s_nop 1
	v_mov_b32_dpp v248, v249 quad_perm:[0,1,2,3] row_mask:0xf bank_mask:0xc
	ds_bpermute_b32 v249, v250, v248
	s_waitcnt lgkmcnt(0)
	v_add_f32_e32 v248, v248, v249
	ds_bpermute_b32 v249, v251, v248
	v_add_u32_e32 v254, 0x2400, v147
	s_waitcnt lgkmcnt(0)
	v_add_f32_e32 v248, v248, v249
	s_and_saveexec_b64 s[62:63], s[0:1]
	global_store_dword v254, v248, s[6:7]
	s_or_b64 exec, exec, s[62:63]
	v_mov_b32_dpp v240, v24 row_ror:8 row_mask:0xf bank_mask:0xf
	v_mov_b32_dpp v241, v25 row_ror:8 row_mask:0xf bank_mask:0xf
	v_mov_b32_dpp v242, v26 row_ror:8 row_mask:0xf bank_mask:0xf
	v_mov_b32_dpp v243, v27 row_ror:8 row_mask:0xf bank_mask:0xf
	v_mov_b32_dpp v24, v28 row_ror:8 row_mask:0xf bank_mask:0x3
	v_mov_b32_dpp v25, v29 row_ror:8 row_mask:0xf bank_mask:0x3
	v_mov_b32_dpp v26, v30 row_ror:8 row_mask:0xf bank_mask:0x3
	v_mov_b32_dpp v27, v31 row_ror:8 row_mask:0xf bank_mask:0x3
	v_mov_b32_dpp v28, v240 quad_perm:[0,1,2,3] row_mask:0xf bank_mask:0xc
	v_mov_b32_dpp v29, v241 quad_perm:[0,1,2,3] row_mask:0xf bank_mask:0xc
	v_mov_b32_dpp v30, v242 quad_perm:[0,1,2,3] row_mask:0xf bank_mask:0xc
	v_mov_b32_dpp v31, v243 quad_perm:[0,1,2,3] row_mask:0xf bank_mask:0xc
	v_mov_b32_dpp v240, v16 row_ror:8 row_mask:0xf bank_mask:0xf
	v_mov_b32_dpp v241, v17 row_ror:8 row_mask:0xf bank_mask:0xf
	v_mov_b32_dpp v242, v18 row_ror:8 row_mask:0xf bank_mask:0xf
	v_mov_b32_dpp v243, v19 row_ror:8 row_mask:0xf bank_mask:0xf
	v_mov_b32_dpp v16, v20 row_ror:8 row_mask:0xf bank_mask:0x3
	v_mov_b32_dpp v17, v21 row_ror:8 row_mask:0xf bank_mask:0x3
	v_mov_b32_dpp v18, v22 row_ror:8 row_mask:0xf bank_mask:0x3
	v_mov_b32_dpp v19, v23 row_ror:8 row_mask:0xf bank_mask:0x3
	v_mov_b32_dpp v20, v240 quad_perm:[0,1,2,3] row_mask:0xf bank_mask:0xc
	v_mov_b32_dpp v21, v241 quad_perm:[0,1,2,3] row_mask:0xf bank_mask:0xc
	v_mov_b32_dpp v22, v242 quad_perm:[0,1,2,3] row_mask:0xf bank_mask:0xc
	v_mov_b32_dpp v23, v243 quad_perm:[0,1,2,3] row_mask:0xf bank_mask:0xc
	s_waitcnt vmcnt(40)
	v_pk_add_f32 v[28:29], v[28:29], v[172:173]
	v_pk_add_f32 v[30:31], v[30:31], v[174:175]
	v_pk_add_f32 v[24:25], v[24:25], v[176:177]
	v_pk_add_f32 v[26:27], v[26:27], v[178:179]
	v_pk_add_f32 v[20:21], v[20:21], v[180:181]
	v_pk_add_f32 v[22:23], v[22:23], v[182:183]
	v_pk_add_f32 v[16:17], v[16:17], v[184:185]
	v_pk_add_f32 v[18:19], v[18:19], v[186:187]
	v_add_u32_e32 v252, 0xa0000, v144
	v_add_u32_e32 v253, 0x8000, v252
	global_store_dwordx4 v252, v[28:31], s[54:55]
	global_store_dwordx4 v253, v[24:27], s[54:55]
	global_store_dwordx4 v252, v[20:23], s[54:55] offset:512
	global_store_dwordx4 v253, v[16:19], s[54:55] offset:512
	v_cvt_pk_bf16_f32 v240, v28, v29
	v_cvt_pk_bf16_f32 v241, v30, v31
	v_cvt_pk_bf16_f32 v242, v24, v25
	v_cvt_pk_bf16_f32 v243, v26, v27
	v_cvt_pk_bf16_f32 v244, v20, v21
	v_cvt_pk_bf16_f32 v245, v22, v23
	v_cvt_pk_bf16_f32 v246, v16, v17
	v_cvt_pk_bf16_f32 v247, v18, v19
	v_lshrrev_b32_e32 v254, 1, v252
	v_lshrrev_b32_e32 v253, 1, v253
	global_store_dwordx2 v254, v[240:241], s[40:41]
	global_store_dwordx2 v253, v[242:243], s[40:41]
	global_store_dwordx2 v254, v[244:245], s[40:41] offset:256
	global_store_dwordx2 v253, v[246:247], s[40:41] offset:256
	v_mul_f32_e32 v248, v28, v28
	v_mul_f32_e32 v249, v24, v24
	v_fmac_f32_e32 v248, v29, v29
	v_fmac_f32_e32 v249, v25, v25
	v_fmac_f32_e32 v248, v30, v30
	v_fmac_f32_e32 v249, v26, v26
	v_fmac_f32_e32 v248, v31, v31
	v_fmac_f32_e32 v249, v27, v27
	v_fmac_f32_e32 v248, v20, v20
	v_fmac_f32_e32 v249, v16, v16
	v_fmac_f32_e32 v248, v21, v21
	v_fmac_f32_e32 v249, v17, v17
	v_fmac_f32_e32 v248, v22, v22
	v_fmac_f32_e32 v249, v18, v18
	v_fmac_f32_e32 v248, v23, v23
	v_fmac_f32_e32 v249, v19, v19
	s_nop 1
	v_mov_b32_dpp v240, v248 row_ror:8 row_mask:0xf bank_mask:0xf
	v_mov_b32_dpp v241, v249 row_ror:8 row_mask:0xf bank_mask:0xf
	s_nop 0
	v_add_f32_e32 v248, v248, v240
	v_add_f32_e32 v249, v249, v241
	s_nop 1
	v_mov_b32_dpp v248, v249 quad_perm:[0,1,2,3] row_mask:0xf bank_mask:0xc
	ds_bpermute_b32 v249, v250, v248
	s_waitcnt lgkmcnt(0)
; #define PG8_BAR __builtin_amdgcn_s_barrier()
; DI unsigned cvt_pk(float lo, float hi) { const f32x2 v = {lo, hi}; return __builtin_bit_cast(unsigned, __builtin_convertvector(v, bf16v2)); }
; template <class Epi, class Sched, bool ALIGN_EPI = false, bool SP2 = false>
; __device__ __forceinline__ void gemm_phase(PG8_LAS unsigned char* lds, const Gemm g, const Sched& S, const Epi& E) {
;     ...
;         if (!has_next) break;
; #pragma unroll
;         for (int a = 0; a < 2; ++a)
; #pragma unroll
;             for (int b = 0; b < 2; ++b)
; #pragma unroll
;                 for (int m = 0; m < 4; ++m)
; #pragma unroll
;                     for (int n = 0; n < 2; ++n) acc[a][b][m][n] = (f32x4){0.f, 0.f, 0.f, 0.f};
;         cur = nxt; cA = nA; cB = nB; ++ui;
;         if constexpr (ALIGN_EPI) { if (wr == 1) PG8_BAR; }
;     __device__ __forceinline__ void operator()(const f32x4 (&acc)[2][2][4][2], const Unit& u, int wr, int wc, int fr, int fq) const {
;         const int col0 = u.pn * 256 + wc * 32 + 8 * fq, rowbase = u.pm * 256 + wr * 64 + fr;
; #pragma unroll
;         for (int ai = 0; ai < 2; ++ai)
; #pragma unroll
;             for (int m = 0; m < 4; ++m) {
;                 const int row = rowbase + ai * 128 + m * 16; const size_t off = (size_t)row * DM + col0;
;                 float q = 0.f;
; #pragma unroll
;                 for (int bj = 0; bj < 2; ++bj) {
;                     const f32x4 r0 = *(const f32x4*)(resid + off + bj * 128), r1 = *(const f32x4*)(resid + off + bj * 128 + 4);
;                     const f32x4 o0 = r0 + acc[ai][bj][m][0], o1 = r1 + acc[ai][bj][m][1];
;                     *(f32x4*)(out + off + bj * 128) = o0; *(f32x4*)(out + off + bj * 128 + 4) = o1;
;                     if (xb) {
;                         u32x4 w; w.x = cvt_pk(o0[0], o0[1]); w.y = cvt_pk(o0[2], o0[3]); w.z = cvt_pk(o1[0], o1[1]); w.w = cvt_pk(o1[2], o1[3]);
;                         *(u32x4*)(xb + off + bj * 128) = w;
;                         q += (o0[0] * o0[0] + o0[1] * o0[1]) + (o0[2] * o0[2] + o0[3] * o0[3]) + (o1[0] * o1[0] + o1[1] * o1[1]) + (o1[2] * o1[2] + o1[3] * o1[3]);
;                     }
;                 }
;                 if (xb) { q += __shfl_xor(q, 16); q += __shfl_xor(q, 32); if (fq == 0) ssq[(size_t)row * 16 + u.pn * 4 + wc] = q; }
;             }
;     }
	v_add_f32_e32 v248, v248, v249
	ds_bpermute_b32 v249, v251, v248
	v_add_u32_e32 v254, 0x2800, v147
	s_waitcnt lgkmcnt(0)
	v_add_f32_e32 v248, v248, v249
	s_and_saveexec_b64 s[62:63], s[0:1]
	global_store_dword v254, v248, s[6:7]
	s_or_b64 exec, exec, s[62:63]
	v_mov_b32_dpp v240, v8 row_ror:8 row_mask:0xf bank_mask:0xf
	v_mov_b32_dpp v241, v9 row_ror:8 row_mask:0xf bank_mask:0xf
	v_mov_b32_dpp v242, v10 row_ror:8 row_mask:0xf bank_mask:0xf
	v_mov_b32_dpp v243, v11 row_ror:8 row_mask:0xf bank_mask:0xf
	v_mov_b32_dpp v8, v12 row_ror:8 row_mask:0xf bank_mask:0x3
	v_mov_b32_dpp v9, v13 row_ror:8 row_mask:0xf bank_mask:0x3
	v_mov_b32_dpp v10, v14 row_ror:8 row_mask:0xf bank_mask:0x3
	v_mov_b32_dpp v11, v15 row_ror:8 row_mask:0xf bank_mask:0x3
	v_mov_b32_dpp v12, v240 quad_perm:[0,1,2,3] row_mask:0xf bank_mask:0xc
	v_mov_b32_dpp v13, v241 quad_perm:[0,1,2,3] row_mask:0xf bank_mask:0xc
	v_mov_b32_dpp v14, v242 quad_perm:[0,1,2,3] row_mask:0xf bank_mask:0xc
	v_mov_b32_dpp v15, v243 quad_perm:[0,1,2,3] row_mask:0xf bank_mask:0xc
	v_mov_b32_dpp v240, v0 row_ror:8 row_mask:0xf bank_mask:0xf
	v_mov_b32_dpp v241, v1 row_ror:8 row_mask:0xf bank_mask:0xf
	v_mov_b32_dpp v242, v2 row_ror:8 row_mask:0xf bank_mask:0xf
	v_mov_b32_dpp v243, v3 row_ror:8 row_mask:0xf bank_mask:0xf
	v_mov_b32_dpp v0, v4 row_ror:8 row_mask:0xf bank_mask:0x3
	v_mov_b32_dpp v1, v5 row_ror:8 row_mask:0xf bank_mask:0x3
	v_mov_b32_dpp v2, v6 row_ror:8 row_mask:0xf bank_mask:0x3
	v_mov_b32_dpp v3, v7 row_ror:8 row_mask:0xf bank_mask:0x3
	v_mov_b32_dpp v4, v240 quad_perm:[0,1,2,3] row_mask:0xf bank_mask:0xc
	v_mov_b32_dpp v5, v241 quad_perm:[0,1,2,3] row_mask:0xf bank_mask:0xc
	v_mov_b32_dpp v6, v242 quad_perm:[0,1,2,3] row_mask:0xf bank_mask:0xc
	v_mov_b32_dpp v7, v243 quad_perm:[0,1,2,3] row_mask:0xf bank_mask:0xc
	s_waitcnt vmcnt(36)
	v_pk_add_f32 v[12:13], v[12:13], v[188:189]
	v_pk_add_f32 v[14:15], v[14:15], v[190:191]
	v_pk_add_f32 v[8:9], v[8:9], v[192:193]
	v_pk_add_f32 v[10:11], v[10:11], v[194:195]
	v_pk_add_f32 v[4:5], v[4:5], v[196:197]
	v_pk_add_f32 v[6:7], v[6:7], v[198:199]
	v_pk_add_f32 v[0:1], v[0:1], v[200:201]
	v_pk_add_f32 v[2:3], v[2:3], v[202:203]
	v_add_u32_e32 v252, 0xb0000, v144
	v_add_u32_e32 v253, 0x8000, v252
	global_store_dwordx4 v252, v[12:15], s[54:55]
	global_store_dwordx4 v253, v[8:11], s[54:55]
	global_store_dwordx4 v252, v[4:7], s[54:55] offset:512
	global_store_dwordx4 v253, v[0:3], s[54:55] offset:512
	v_cvt_pk_bf16_f32 v240, v12, v13
	v_cvt_pk_bf16_f32 v241, v14, v15
	v_cvt_pk_bf16_f32 v242, v8, v9
	v_cvt_pk_bf16_f32 v243, v10, v11
	v_cvt_pk_bf16_f32 v244, v4, v5
	v_cvt_pk_bf16_f32 v245, v6, v7
	v_cvt_pk_bf16_f32 v246, v0, v1
	v_cvt_pk_bf16_f32 v247, v2, v3
	v_lshrrev_b32_e32 v254, 1, v252
	v_lshrrev_b32_e32 v253, 1, v253
	global_store_dwordx2 v254, v[240:241], s[40:41]
	global_store_dwordx2 v253, v[242:243], s[40:41]
	global_store_dwordx2 v254, v[244:245], s[40:41] offset:256
	global_store_dwordx2 v253, v[246:247], s[40:41] offset:256
	v_mul_f32_e32 v248, v12, v12
	v_mul_f32_e32 v249, v8, v8
	v_fmac_f32_e32 v248, v13, v13
	v_fmac_f32_e32 v249, v9, v9
	v_fmac_f32_e32 v248, v14, v14
	v_fmac_f32_e32 v249, v10, v10
	v_fmac_f32_e32 v248, v15, v15
	v_fmac_f32_e32 v249, v11, v11
	v_fmac_f32_e32 v248, v4, v4
	v_fmac_f32_e32 v249, v0, v0
	v_fmac_f32_e32 v248, v5, v5
	v_fmac_f32_e32 v249, v1, v1
	v_fmac_f32_e32 v248, v6, v6
	v_fmac_f32_e32 v249, v2, v2
	v_fmac_f32_e32 v248, v7, v7
	v_fmac_f32_e32 v249, v3, v3
	s_nop 1
	v_mov_b32_dpp v240, v248 row_ror:8 row_mask:0xf bank_mask:0xf
	v_mov_b32_dpp v241, v249 row_ror:8 row_mask:0xf bank_mask:0xf
	s_nop 0
	v_add_f32_e32 v248, v248, v240
	v_add_f32_e32 v249, v249, v241
	s_nop 1
	v_mov_b32_dpp v248, v249 quad_perm:[0,1,2,3] row_mask:0xf bank_mask:0xc
	ds_bpermute_b32 v249, v250, v248
	s_waitcnt lgkmcnt(0)
	v_add_f32_e32 v248, v248, v249
	ds_bpermute_b32 v249, v251, v248
	v_add_u32_e32 v254, 0x2c00, v147
	s_waitcnt lgkmcnt(0)
	v_add_f32_e32 v248, v248, v249
	s_and_saveexec_b64 s[62:63], s[0:1]
	global_store_dword v254, v248, s[6:7]
	s_or_b64 exec, exec, s[62:63]
	s_andn2_b64 vcc, exec, s[4:5]
	s_mov_b64 s[4:5], -1
	s_cbranch_vccnz .LBB0_742
	s_andn2_b64 vcc, exec, s[10:11]
	s_cbranch_vccnz .LBB0_741
	s_barrier
	s_branch .LBB0_741
